# last layer ffn-out residual epilogue: dead stores removed (bf16 copy of x and sum-of-squares slices are only read by a next layer), lean pipelined copy for l == 1
# speedup vs baseline: 1.0141x; 1.0141x over previous
; #define LAS __attribute__((address_space(3)))
; __device__ __forceinline__ unsigned cvt_pk_bf16(float lo, float hi) { unsigned r; asm volatile("v_cvt_pk_bf16_f32 %0, %1, %2" : "=v"(r) : "v"(lo), "v"(hi)); return r; }
;     __device__ __forceinline__ void operator()(const f32x4 (&acc)[2][2][4][2], const pg8::Unit& u, int wr, int wc, int fr, int fq, LAS unsigned char*) const {
;         const int row0 = u.pm * 256 + wr * 64 + fr, col0 = u.pn * 256 + wc * 32 + 4 * fq;
; #pragma unroll
;         for (int ai = 0; ai < 2; ++ai)
; #pragma unroll
;             for (int m = 0; m < 4; ++m) {
;                 const int row = row0 + ai * 128 + m * 16; const size_t off = (size_t)row * DM + col0; float q = 0.f;
; #pragma unroll
;                 for (int bj = 0; bj < 2; ++bj)
; #pragma unroll
;                     for (int n = 0; n < 2; ++n) { const size_t o = off + bj * 128 + n * 16; const f32x4 xv = *(const f32x4*)(xin + o) + acc[ai][bj][m][n]; *(f32x4*)(xout + o) = xv;
;                         q += (xv[0] * xv[0] + xv[1] * xv[1]) + (xv[2] * xv[2] + xv[3] * xv[3]);
;                         u32x2 w; w.x = cvt_pk_bf16(xv[0], xv[1]); w.y = cvt_pk_bf16(xv[2], xv[3]); *(u32x2*)(xb + o) = w; }
;                 q += __shfl_xor(q, 16); q += __shfl_xor(q, 32);
;                 if (fq == 0) ssq[(size_t)row * 16 + u.pn * 4 + wc] = q;
;             }
.LBB0_421:
	s_cmp_eq_u32 s46, 1
	s_cbranch_scc1 .Lepi8_lean
	v_lshl_add_u32 v136, s68, 8, v142
	v_lshl_or_b32 v137, s28, 8, v144
	s_lshl_b32 s50, s28, 4
	s_lshl_b32 s51, s59, 2
	s_add_u32 s50, s50, s51
	v_lshl_add_u32 v139, v136, 10, v137
	v_lshl_add_u32 v140, v136, 6, s50
	v_lshlrev_b32_e32 v138, 2, v139
	v_lshlrev_b32_e32 v139, 1, v139
	v_xor_b32_e32 v141, 16, v187
	v_xor_b32_e32 v172, 32, v187
	v_lshlrev_b32_e32 v141, 2, v141
	v_lshlrev_b32_e32 v172, 2, v172
	global_load_dwordx4 v[198:201], v138, s[12:13]
	global_load_dwordx4 v[202:205], v138, s[12:13] offset:64
	global_load_dwordx4 v[206:209], v138, s[12:13] offset:512
	global_load_dwordx4 v[210:213], v138, s[12:13] offset:576
	v_add_u32_e32 v173, 0x10000, v138
	global_load_dwordx4 v[214:217], v173, s[12:13]
	global_load_dwordx4 v[218:221], v173, s[12:13] offset:64
	global_load_dwordx4 v[222:225], v173, s[12:13] offset:512
	global_load_dwordx4 v[226:229], v173, s[12:13] offset:576
	v_add_u32_e32 v173, 0x20000, v138
	global_load_dwordx4 v[156:159], v173, s[12:13]
	global_load_dwordx4 v[160:163], v173, s[12:13] offset:64
	global_load_dwordx4 v[164:167], v173, s[12:13] offset:512
	global_load_dwordx4 v[168:171], v173, s[12:13] offset:576
	v_mov_b32_e32 v174, v138
	v_mov_b32_e32 v175, v139
	v_mov_b32_e32 v176, v140
	s_waitcnt vmcnt(11)
	v_pk_add_f32 v[200:201], v[128:129], v[200:201]
	v_pk_add_f32 v[198:199], v[126:127], v[198:199]
	global_store_dwordx4 v174, v[198:201], s[84:85]
	v_mul_f32_e32 v178, v201, v201
	v_mul_f32_e32 v177, v199, v199
	v_fmac_f32_e32 v177, v198, v198
	v_fmac_f32_e32 v178, v200, v200
	v_cvt_pk_bf16_f32 v180, v198, v199
	v_cvt_pk_bf16_f32 v181, v200, v201
	v_add_f32_e32 v179, v177, v178
	global_store_dwordx2 v175, v[180:181], s[18:19]
	s_waitcnt vmcnt(12)
	v_pk_add_f32 v[204:205], v[124:125], v[204:205]
	v_pk_add_f32 v[202:203], v[122:123], v[202:203]
	global_store_dwordx4 v174, v[202:205], s[84:85] offset:64
	v_mul_f32_e32 v178, v205, v205
	v_mul_f32_e32 v177, v203, v203
	v_fmac_f32_e32 v177, v202, v202
	v_fmac_f32_e32 v178, v204, v204
	v_cvt_pk_bf16_f32 v182, v202, v203
	v_cvt_pk_bf16_f32 v183, v204, v205
	v_add_f32_e32 v177, v177, v178
	v_add_f32_e32 v179, v179, v177
	global_store_dwordx2 v175, v[182:183], s[18:19] offset:32
	s_waitcnt vmcnt(13)
	v_pk_add_f32 v[208:209], v[120:121], v[208:209]
	v_pk_add_f32 v[206:207], v[118:119], v[206:207]
	global_store_dwordx4 v174, v[206:209], s[84:85] offset:512
	v_mul_f32_e32 v178, v209, v209
	v_mul_f32_e32 v177, v207, v207
	v_fmac_f32_e32 v177, v206, v206
	v_fmac_f32_e32 v178, v208, v208
	v_cvt_pk_bf16_f32 v180, v206, v207
	v_cvt_pk_bf16_f32 v181, v208, v209
	v_add_f32_e32 v177, v177, v178
	v_add_f32_e32 v179, v179, v177
	global_store_dwordx2 v175, v[180:181], s[18:19] offset:256
	s_waitcnt vmcnt(14)
	v_pk_add_f32 v[212:213], v[116:117], v[212:213]
	v_pk_add_f32 v[210:211], v[114:115], v[210:211]
	global_store_dwordx4 v174, v[210:213], s[84:85] offset:576
	v_mul_f32_e32 v178, v213, v213
	v_mul_f32_e32 v177, v211, v211
	v_fmac_f32_e32 v177, v210, v210
	v_fmac_f32_e32 v178, v212, v212
	v_cvt_pk_bf16_f32 v182, v210, v211
	v_cvt_pk_bf16_f32 v183, v212, v213
	v_add_f32_e32 v177, v177, v178
	v_add_f32_e32 v179, v179, v177
	global_store_dwordx2 v175, v[182:183], s[18:19] offset:288
	ds_bpermute_b32 v177, v141, v179
	s_waitcnt lgkmcnt(0)
	v_add_f32_e32 v179, v179, v177
	ds_bpermute_b32 v178, v172, v179
	s_waitcnt lgkmcnt(0)
	v_add_f32_e32 v179, v179, v178
	s_and_saveexec_b64 s[52:53], s[4:5]
	global_store_dword v176, v179, s[14:15]
	s_mov_b64 exec, s[52:53]
	v_add_u32_e32 v173, 0x30000, v138
	global_load_dwordx4 v[198:201], v173, s[12:13]
	global_load_dwordx4 v[202:205], v173, s[12:13] offset:64
	global_load_dwordx4 v[206:209], v173, s[12:13] offset:512
	global_load_dwordx4 v[210:213], v173, s[12:13] offset:576
	v_add_u32_e32 v174, 0x10000, v138
	v_add_u32_e32 v175, 0x8000, v139
	v_add_u32_e32 v176, 0x400, v140
	s_waitcnt vmcnt(20)
	v_pk_add_f32 v[216:217], v[112:113], v[216:217]
	v_pk_add_f32 v[214:215], v[110:111], v[214:215]
	global_store_dwordx4 v174, v[214:217], s[84:85]
	v_mul_f32_e32 v178, v217, v217
	v_mul_f32_e32 v177, v215, v215
	v_fmac_f32_e32 v177, v214, v214
	v_fmac_f32_e32 v178, v216, v216
	v_cvt_pk_bf16_f32 v180, v214, v215
	v_cvt_pk_bf16_f32 v181, v216, v217
	v_add_f32_e32 v179, v177, v178
	global_store_dwordx2 v175, v[180:181], s[18:19]
	s_waitcnt vmcnt(21)
	v_pk_add_f32 v[220:221], v[108:109], v[220:221]
	v_pk_add_f32 v[218:219], v[106:107], v[218:219]
	global_store_dwordx4 v174, v[218:221], s[84:85] offset:64
	v_mul_f32_e32 v178, v221, v221
	v_mul_f32_e32 v177, v219, v219
	v_fmac_f32_e32 v177, v218, v218
	v_fmac_f32_e32 v178, v220, v220
	v_cvt_pk_bf16_f32 v182, v218, v219
	v_cvt_pk_bf16_f32 v183, v220, v221
	v_add_f32_e32 v177, v177, v178
	v_add_f32_e32 v179, v179, v177
	global_store_dwordx2 v175, v[182:183], s[18:19] offset:32
	s_waitcnt vmcnt(22)
	v_pk_add_f32 v[224:225], v[104:105], v[224:225]
	v_pk_add_f32 v[222:223], v[102:103], v[222:223]
	global_store_dwordx4 v174, v[222:225], s[84:85] offset:512
	v_mul_f32_e32 v178, v225, v225
	v_mul_f32_e32 v177, v223, v223
	v_fmac_f32_e32 v177, v222, v222
	v_fmac_f32_e32 v178, v224, v224
	v_cvt_pk_bf16_f32 v180, v222, v223
	v_cvt_pk_bf16_f32 v181, v224, v225
	v_add_f32_e32 v177, v177, v178
	v_add_f32_e32 v179, v179, v177
	global_store_dwordx2 v175, v[180:181], s[18:19] offset:256
	s_waitcnt vmcnt(23)
; __device__ __forceinline__ unsigned cvt_pk_bf16(float lo, float hi) { unsigned r; asm volatile("v_cvt_pk_bf16_f32 %0, %1, %2" : "=v"(r) : "v"(lo), "v"(hi)); return r; }
;     __device__ __forceinline__ void operator()(const f32x4 (&acc)[2][2][4][2], const pg8::Unit& u, int wr, int wc, int fr, int fq, LAS unsigned char*) const {
;     ...
;                 const int row = row0 + ai * 128 + m * 16; const size_t off = (size_t)row * DM + col0; float q = 0.f;
; #pragma unroll
;                 for (int bj = 0; bj < 2; ++bj)
; #pragma unroll
;                     for (int n = 0; n < 2; ++n) { const size_t o = off + bj * 128 + n * 16; const f32x4 xv = *(const f32x4*)(xin + o) + acc[ai][bj][m][n]; *(f32x4*)(xout + o) = xv;
;                         q += (xv[0] * xv[0] + xv[1] * xv[1]) + (xv[2] * xv[2] + xv[3] * xv[3]);
;                         u32x2 w; w.x = cvt_pk_bf16(xv[0], xv[1]); w.y = cvt_pk_bf16(xv[2], xv[3]); *(u32x2*)(xb + o) = w; }
;                 q += __shfl_xor(q, 16); q += __shfl_xor(q, 32);
;                 if (fq == 0) ssq[(size_t)row * 16 + u.pn * 4 + wc] = q;
;             }
	v_pk_add_f32 v[228:229], v[100:101], v[228:229]
	v_pk_add_f32 v[226:227], v[98:99], v[226:227]
	global_store_dwordx4 v174, v[226:229], s[84:85] offset:576
	v_mul_f32_e32 v178, v229, v229
	v_mul_f32_e32 v177, v227, v227
	v_fmac_f32_e32 v177, v226, v226
	v_fmac_f32_e32 v178, v228, v228
	v_cvt_pk_bf16_f32 v182, v226, v227
	v_cvt_pk_bf16_f32 v183, v228, v229
	v_add_f32_e32 v177, v177, v178
	v_add_f32_e32 v179, v179, v177
	global_store_dwordx2 v175, v[182:183], s[18:19] offset:288
	ds_bpermute_b32 v177, v141, v179
	s_waitcnt lgkmcnt(0)
	v_add_f32_e32 v179, v179, v177
	ds_bpermute_b32 v178, v172, v179
	s_waitcnt lgkmcnt(0)
	v_add_f32_e32 v179, v179, v178
	s_and_saveexec_b64 s[52:53], s[4:5]
	global_store_dword v176, v179, s[14:15]
	s_mov_b64 exec, s[52:53]
	v_add_u32_e32 v173, 0x80000, v138
	global_load_dwordx4 v[214:217], v173, s[12:13]
	global_load_dwordx4 v[218:221], v173, s[12:13] offset:64
	global_load_dwordx4 v[222:225], v173, s[12:13] offset:512
	global_load_dwordx4 v[226:229], v173, s[12:13] offset:576
	v_add_u32_e32 v174, 0x20000, v138
	v_add_u32_e32 v175, 0x10000, v139
	v_add_u32_e32 v176, 0x800, v140
	s_waitcnt vmcnt(29)
	v_pk_add_f32 v[158:159], v[96:97], v[158:159]
	v_pk_add_f32 v[156:157], v[94:95], v[156:157]
	global_store_dwordx4 v174, v[156:159], s[84:85]
	v_mul_f32_e32 v178, v159, v159
	v_mul_f32_e32 v177, v157, v157
	v_fmac_f32_e32 v177, v156, v156
	v_fmac_f32_e32 v178, v158, v158
	v_cvt_pk_bf16_f32 v180, v156, v157
	v_cvt_pk_bf16_f32 v181, v158, v159
	v_add_f32_e32 v179, v177, v178
	global_store_dwordx2 v175, v[180:181], s[18:19]
	s_waitcnt vmcnt(30)
	v_pk_add_f32 v[162:163], v[92:93], v[162:163]
	v_pk_add_f32 v[160:161], v[90:91], v[160:161]
	global_store_dwordx4 v174, v[160:163], s[84:85] offset:64
	v_mul_f32_e32 v178, v163, v163
	v_mul_f32_e32 v177, v161, v161
	v_fmac_f32_e32 v177, v160, v160
	v_fmac_f32_e32 v178, v162, v162
	v_cvt_pk_bf16_f32 v182, v160, v161
	v_cvt_pk_bf16_f32 v183, v162, v163
	v_add_f32_e32 v177, v177, v178
	v_add_f32_e32 v179, v179, v177
	global_store_dwordx2 v175, v[182:183], s[18:19] offset:32
	s_waitcnt vmcnt(31)
	v_pk_add_f32 v[166:167], v[88:89], v[166:167]
	v_pk_add_f32 v[164:165], v[86:87], v[164:165]
	global_store_dwordx4 v174, v[164:167], s[84:85] offset:512
	v_mul_f32_e32 v178, v167, v167
	v_mul_f32_e32 v177, v165, v165
	v_fmac_f32_e32 v177, v164, v164
	v_fmac_f32_e32 v178, v166, v166
	v_cvt_pk_bf16_f32 v180, v164, v165
	v_cvt_pk_bf16_f32 v181, v166, v167
	v_add_f32_e32 v177, v177, v178
	v_add_f32_e32 v179, v179, v177
	global_store_dwordx2 v175, v[180:181], s[18:19] offset:256
	s_waitcnt vmcnt(32)
	v_pk_add_f32 v[170:171], v[84:85], v[170:171]
	v_pk_add_f32 v[168:169], v[82:83], v[168:169]
	global_store_dwordx4 v174, v[168:171], s[84:85] offset:576
	v_mul_f32_e32 v178, v171, v171
	v_mul_f32_e32 v177, v169, v169
	v_fmac_f32_e32 v177, v168, v168
	v_fmac_f32_e32 v178, v170, v170
	v_cvt_pk_bf16_f32 v182, v168, v169
	v_cvt_pk_bf16_f32 v183, v170, v171
	v_add_f32_e32 v177, v177, v178
	v_add_f32_e32 v179, v179, v177
	global_store_dwordx2 v175, v[182:183], s[18:19] offset:288
	ds_bpermute_b32 v177, v141, v179
	s_waitcnt lgkmcnt(0)
	v_add_f32_e32 v179, v179, v177
	ds_bpermute_b32 v178, v172, v179
	s_waitcnt lgkmcnt(0)
	v_add_f32_e32 v179, v179, v178
	s_and_saveexec_b64 s[52:53], s[4:5]
	global_store_dword v176, v179, s[14:15]
	s_mov_b64 exec, s[52:53]
	v_add_u32_e32 v173, 0x90000, v138
	global_load_dwordx4 v[156:159], v173, s[12:13]
	global_load_dwordx4 v[160:163], v173, s[12:13] offset:64
	global_load_dwordx4 v[164:167], v173, s[12:13] offset:512
	global_load_dwordx4 v[168:171], v173, s[12:13] offset:576
	v_add_u32_e32 v174, 0x30000, v138
	v_add_u32_e32 v175, 0x18000, v139
	v_add_u32_e32 v176, 0xc00, v140
	s_waitcnt vmcnt(29)
	v_pk_add_f32 v[200:201], v[80:81], v[200:201]
	v_pk_add_f32 v[198:199], v[78:79], v[198:199]
	global_store_dwordx4 v174, v[198:201], s[84:85]
	v_mul_f32_e32 v178, v201, v201
	v_mul_f32_e32 v177, v199, v199
	v_fmac_f32_e32 v177, v198, v198
	v_fmac_f32_e32 v178, v200, v200
	v_cvt_pk_bf16_f32 v180, v198, v199
	v_cvt_pk_bf16_f32 v181, v200, v201
	v_add_f32_e32 v179, v177, v178
	global_store_dwordx2 v175, v[180:181], s[18:19]
	s_waitcnt vmcnt(30)
	v_pk_add_f32 v[204:205], v[76:77], v[204:205]
	v_pk_add_f32 v[202:203], v[74:75], v[202:203]
	global_store_dwordx4 v174, v[202:205], s[84:85] offset:64
	v_mul_f32_e32 v178, v205, v205
	v_mul_f32_e32 v177, v203, v203
	v_fmac_f32_e32 v177, v202, v202
	v_fmac_f32_e32 v178, v204, v204
	v_cvt_pk_bf16_f32 v182, v202, v203
	v_cvt_pk_bf16_f32 v183, v204, v205
	v_add_f32_e32 v177, v177, v178
	v_add_f32_e32 v179, v179, v177
	global_store_dwordx2 v175, v[182:183], s[18:19] offset:32
	s_waitcnt vmcnt(31)
	v_pk_add_f32 v[208:209], v[72:73], v[208:209]
	v_pk_add_f32 v[206:207], v[70:71], v[206:207]
	global_store_dwordx4 v174, v[206:209], s[84:85] offset:512
	v_mul_f32_e32 v178, v209, v209
	v_mul_f32_e32 v177, v207, v207
	v_fmac_f32_e32 v177, v206, v206
	v_fmac_f32_e32 v178, v208, v208
	v_cvt_pk_bf16_f32 v180, v206, v207
	v_cvt_pk_bf16_f32 v181, v208, v209
	v_add_f32_e32 v177, v177, v178
	v_add_f32_e32 v179, v179, v177
	global_store_dwordx2 v175, v[180:181], s[18:19] offset:256
	s_waitcnt vmcnt(32)
	v_pk_add_f32 v[212:213], v[68:69], v[212:213]
	v_pk_add_f32 v[210:211], v[66:67], v[210:211]
	global_store_dwordx4 v174, v[210:213], s[84:85] offset:576
	v_mul_f32_e32 v178, v213, v213
	v_mul_f32_e32 v177, v211, v211
	v_fmac_f32_e32 v177, v210, v210
	v_fmac_f32_e32 v178, v212, v212
	v_cvt_pk_bf16_f32 v182, v210, v211
	v_cvt_pk_bf16_f32 v183, v212, v213
	v_add_f32_e32 v177, v177, v178
	v_add_f32_e32 v179, v179, v177
	global_store_dwordx2 v175, v[182:183], s[18:19] offset:288
	ds_bpermute_b32 v177, v141, v179
	s_waitcnt lgkmcnt(0)
; __device__ __forceinline__ unsigned cvt_pk_bf16(float lo, float hi) { unsigned r; asm volatile("v_cvt_pk_bf16_f32 %0, %1, %2" : "=v"(r) : "v"(lo), "v"(hi)); return r; }
;     __device__ __forceinline__ void operator()(const f32x4 (&acc)[2][2][4][2], const pg8::Unit& u, int wr, int wc, int fr, int fq, LAS unsigned char*) const {
;     ...
;                 const int row = row0 + ai * 128 + m * 16; const size_t off = (size_t)row * DM + col0; float q = 0.f;
; #pragma unroll
;                 for (int bj = 0; bj < 2; ++bj)
; #pragma unroll
;                     for (int n = 0; n < 2; ++n) { const size_t o = off + bj * 128 + n * 16; const f32x4 xv = *(const f32x4*)(xin + o) + acc[ai][bj][m][n]; *(f32x4*)(xout + o) = xv;
;                         q += (xv[0] * xv[0] + xv[1] * xv[1]) + (xv[2] * xv[2] + xv[3] * xv[3]);
;                         u32x2 w; w.x = cvt_pk_bf16(xv[0], xv[1]); w.y = cvt_pk_bf16(xv[2], xv[3]); *(u32x2*)(xb + o) = w; }
;                 q += __shfl_xor(q, 16); q += __shfl_xor(q, 32);
;                 if (fq == 0) ssq[(size_t)row * 16 + u.pn * 4 + wc] = q;
;             }
	v_add_f32_e32 v179, v179, v177
	ds_bpermute_b32 v178, v172, v179
	s_waitcnt lgkmcnt(0)
	v_add_f32_e32 v179, v179, v178
	s_and_saveexec_b64 s[52:53], s[4:5]
	global_store_dword v176, v179, s[14:15]
	s_mov_b64 exec, s[52:53]
	v_add_u32_e32 v173, 0xa0000, v138
	global_load_dwordx4 v[198:201], v173, s[12:13]
	global_load_dwordx4 v[202:205], v173, s[12:13] offset:64
	global_load_dwordx4 v[206:209], v173, s[12:13] offset:512
	global_load_dwordx4 v[210:213], v173, s[12:13] offset:576
	v_add_u32_e32 v174, 0x80000, v138
	v_add_u32_e32 v175, 0x40000, v139
	v_add_u32_e32 v176, 0x2000, v140
	s_waitcnt vmcnt(29)
	v_pk_add_f32 v[216:217], v[64:65], v[216:217]
	v_pk_add_f32 v[214:215], v[62:63], v[214:215]
	global_store_dwordx4 v174, v[214:217], s[84:85]
	v_mul_f32_e32 v178, v217, v217
	v_mul_f32_e32 v177, v215, v215
	v_fmac_f32_e32 v177, v214, v214
	v_fmac_f32_e32 v178, v216, v216
	v_cvt_pk_bf16_f32 v180, v214, v215
	v_cvt_pk_bf16_f32 v181, v216, v217
	v_add_f32_e32 v179, v177, v178
	global_store_dwordx2 v175, v[180:181], s[18:19]
	s_waitcnt vmcnt(30)
	v_pk_add_f32 v[220:221], v[60:61], v[220:221]
	v_pk_add_f32 v[218:219], v[58:59], v[218:219]
	global_store_dwordx4 v174, v[218:221], s[84:85] offset:64
	v_mul_f32_e32 v178, v221, v221
	v_mul_f32_e32 v177, v219, v219
	v_fmac_f32_e32 v177, v218, v218
	v_fmac_f32_e32 v178, v220, v220
	v_cvt_pk_bf16_f32 v182, v218, v219
	v_cvt_pk_bf16_f32 v183, v220, v221
	v_add_f32_e32 v177, v177, v178
	v_add_f32_e32 v179, v179, v177
	global_store_dwordx2 v175, v[182:183], s[18:19] offset:32
	s_waitcnt vmcnt(31)
	v_pk_add_f32 v[224:225], v[56:57], v[224:225]
	v_pk_add_f32 v[222:223], v[54:55], v[222:223]
	global_store_dwordx4 v174, v[222:225], s[84:85] offset:512
	v_mul_f32_e32 v178, v225, v225
	v_mul_f32_e32 v177, v223, v223
	v_fmac_f32_e32 v177, v222, v222
	v_fmac_f32_e32 v178, v224, v224
	v_cvt_pk_bf16_f32 v180, v222, v223
	v_cvt_pk_bf16_f32 v181, v224, v225
	v_add_f32_e32 v177, v177, v178
	v_add_f32_e32 v179, v179, v177
	global_store_dwordx2 v175, v[180:181], s[18:19] offset:256
	s_waitcnt vmcnt(32)
	v_pk_add_f32 v[228:229], v[52:53], v[228:229]
	v_pk_add_f32 v[226:227], v[50:51], v[226:227]
	global_store_dwordx4 v174, v[226:229], s[84:85] offset:576
	v_mul_f32_e32 v178, v229, v229
	v_mul_f32_e32 v177, v227, v227
	v_fmac_f32_e32 v177, v226, v226
	v_fmac_f32_e32 v178, v228, v228
	v_cvt_pk_bf16_f32 v182, v226, v227
	v_cvt_pk_bf16_f32 v183, v228, v229
	v_add_f32_e32 v177, v177, v178
	v_add_f32_e32 v179, v179, v177
	global_store_dwordx2 v175, v[182:183], s[18:19] offset:288
	ds_bpermute_b32 v177, v141, v179
	s_waitcnt lgkmcnt(0)
	v_add_f32_e32 v179, v179, v177
	ds_bpermute_b32 v178, v172, v179
	s_waitcnt lgkmcnt(0)
	v_add_f32_e32 v179, v179, v178
	s_and_saveexec_b64 s[52:53], s[4:5]
	global_store_dword v176, v179, s[14:15]
	s_mov_b64 exec, s[52:53]
	v_add_u32_e32 v173, 0xb0000, v138
	global_load_dwordx4 v[214:217], v173, s[12:13]
	global_load_dwordx4 v[218:221], v173, s[12:13] offset:64
	global_load_dwordx4 v[222:225], v173, s[12:13] offset:512
	global_load_dwordx4 v[226:229], v173, s[12:13] offset:576
	v_add_u32_e32 v174, 0x90000, v138
	v_add_u32_e32 v175, 0x48000, v139
	v_add_u32_e32 v176, 0x2400, v140
	s_waitcnt vmcnt(29)
	v_pk_add_f32 v[158:159], v[48:49], v[158:159]
	v_pk_add_f32 v[156:157], v[46:47], v[156:157]
	global_store_dwordx4 v174, v[156:159], s[84:85]
	v_mul_f32_e32 v178, v159, v159
	v_mul_f32_e32 v177, v157, v157
	v_fmac_f32_e32 v177, v156, v156
	v_fmac_f32_e32 v178, v158, v158
	v_cvt_pk_bf16_f32 v180, v156, v157
	v_cvt_pk_bf16_f32 v181, v158, v159
	v_add_f32_e32 v179, v177, v178
	global_store_dwordx2 v175, v[180:181], s[18:19]
	s_waitcnt vmcnt(30)
	v_pk_add_f32 v[162:163], v[44:45], v[162:163]
	v_pk_add_f32 v[160:161], v[42:43], v[160:161]
	global_store_dwordx4 v174, v[160:163], s[84:85] offset:64
	v_mul_f32_e32 v178, v163, v163
	v_mul_f32_e32 v177, v161, v161
	v_fmac_f32_e32 v177, v160, v160
	v_fmac_f32_e32 v178, v162, v162
	v_cvt_pk_bf16_f32 v182, v160, v161
	v_cvt_pk_bf16_f32 v183, v162, v163
	v_add_f32_e32 v177, v177, v178
	v_add_f32_e32 v179, v179, v177
	global_store_dwordx2 v175, v[182:183], s[18:19] offset:32
	s_waitcnt vmcnt(31)
	v_pk_add_f32 v[166:167], v[40:41], v[166:167]
	v_pk_add_f32 v[164:165], v[38:39], v[164:165]
	global_store_dwordx4 v174, v[164:167], s[84:85] offset:512
	v_mul_f32_e32 v178, v167, v167
	v_mul_f32_e32 v177, v165, v165
	v_fmac_f32_e32 v177, v164, v164
	v_fmac_f32_e32 v178, v166, v166
	v_cvt_pk_bf16_f32 v180, v164, v165
	v_cvt_pk_bf16_f32 v181, v166, v167
	v_add_f32_e32 v177, v177, v178
	v_add_f32_e32 v179, v179, v177
	global_store_dwordx2 v175, v[180:181], s[18:19] offset:256
	s_waitcnt vmcnt(32)
	v_pk_add_f32 v[170:171], v[36:37], v[170:171]
	v_pk_add_f32 v[168:169], v[34:35], v[168:169]
	global_store_dwordx4 v174, v[168:171], s[84:85] offset:576
	v_mul_f32_e32 v178, v171, v171
	v_mul_f32_e32 v177, v169, v169
	v_fmac_f32_e32 v177, v168, v168
	v_fmac_f32_e32 v178, v170, v170
	v_cvt_pk_bf16_f32 v182, v168, v169
	v_cvt_pk_bf16_f32 v183, v170, v171
	v_add_f32_e32 v177, v177, v178
	v_add_f32_e32 v179, v179, v177
	global_store_dwordx2 v175, v[182:183], s[18:19] offset:288
	ds_bpermute_b32 v177, v141, v179
	s_waitcnt lgkmcnt(0)
	v_add_f32_e32 v179, v179, v177
	ds_bpermute_b32 v178, v172, v179
	s_waitcnt lgkmcnt(0)
	v_add_f32_e32 v179, v179, v178
	s_and_saveexec_b64 s[52:53], s[4:5]
	global_store_dword v176, v179, s[14:15]
	s_mov_b64 exec, s[52:53]
	v_add_u32_e32 v174, 0xa0000, v138
	v_add_u32_e32 v175, 0x50000, v139
	v_add_u32_e32 v176, 0x2800, v140
	s_waitcnt vmcnt(25)
; __device__ __forceinline__ unsigned cvt_pk_bf16(float lo, float hi) { unsigned r; asm volatile("v_cvt_pk_bf16_f32 %0, %1, %2" : "=v"(r) : "v"(lo), "v"(hi)); return r; }
;     __device__ __forceinline__ void operator()(const f32x4 (&acc)[2][2][4][2], const pg8::Unit& u, int wr, int wc, int fr, int fq, LAS unsigned char*) const {
;     ...
;                 const int row = row0 + ai * 128 + m * 16; const size_t off = (size_t)row * DM + col0; float q = 0.f;
; #pragma unroll
;                 for (int bj = 0; bj < 2; ++bj)
; #pragma unroll
;                     for (int n = 0; n < 2; ++n) { const size_t o = off + bj * 128 + n * 16; const f32x4 xv = *(const f32x4*)(xin + o) + acc[ai][bj][m][n]; *(f32x4*)(xout + o) = xv;
;                         q += (xv[0] * xv[0] + xv[1] * xv[1]) + (xv[2] * xv[2] + xv[3] * xv[3]);
;                         u32x2 w; w.x = cvt_pk_bf16(xv[0], xv[1]); w.y = cvt_pk_bf16(xv[2], xv[3]); *(u32x2*)(xb + o) = w; }
;                 q += __shfl_xor(q, 16); q += __shfl_xor(q, 32);
;                 if (fq == 0) ssq[(size_t)row * 16 + u.pn * 4 + wc] = q;
;             }
	v_pk_add_f32 v[200:201], v[32:33], v[200:201]
	v_pk_add_f32 v[198:199], v[30:31], v[198:199]
	global_store_dwordx4 v174, v[198:201], s[84:85]
	v_mul_f32_e32 v178, v201, v201
	v_mul_f32_e32 v177, v199, v199
	v_fmac_f32_e32 v177, v198, v198
	v_fmac_f32_e32 v178, v200, v200
	v_cvt_pk_bf16_f32 v180, v198, v199
	v_cvt_pk_bf16_f32 v181, v200, v201
	v_add_f32_e32 v179, v177, v178
	global_store_dwordx2 v175, v[180:181], s[18:19]
	s_waitcnt vmcnt(26)
	v_pk_add_f32 v[204:205], v[28:29], v[204:205]
	v_pk_add_f32 v[202:203], v[26:27], v[202:203]
	global_store_dwordx4 v174, v[202:205], s[84:85] offset:64
	v_mul_f32_e32 v178, v205, v205
	v_mul_f32_e32 v177, v203, v203
	v_fmac_f32_e32 v177, v202, v202
	v_fmac_f32_e32 v178, v204, v204
	v_cvt_pk_bf16_f32 v182, v202, v203
	v_cvt_pk_bf16_f32 v183, v204, v205
	v_add_f32_e32 v177, v177, v178
	v_add_f32_e32 v179, v179, v177
	global_store_dwordx2 v175, v[182:183], s[18:19] offset:32
	s_waitcnt vmcnt(27)
	v_pk_add_f32 v[208:209], v[24:25], v[208:209]
	v_pk_add_f32 v[206:207], v[22:23], v[206:207]
	global_store_dwordx4 v174, v[206:209], s[84:85] offset:512
	v_mul_f32_e32 v178, v209, v209
	v_mul_f32_e32 v177, v207, v207
	v_fmac_f32_e32 v177, v206, v206
	v_fmac_f32_e32 v178, v208, v208
	v_cvt_pk_bf16_f32 v180, v206, v207
	v_cvt_pk_bf16_f32 v181, v208, v209
	v_add_f32_e32 v177, v177, v178
	v_add_f32_e32 v179, v179, v177
	global_store_dwordx2 v175, v[180:181], s[18:19] offset:256
	s_waitcnt vmcnt(28)
	v_pk_add_f32 v[212:213], v[20:21], v[212:213]
	v_pk_add_f32 v[210:211], v[18:19], v[210:211]
	global_store_dwordx4 v174, v[210:213], s[84:85] offset:576
	v_mul_f32_e32 v178, v213, v213
	v_mul_f32_e32 v177, v211, v211
	v_fmac_f32_e32 v177, v210, v210
	v_fmac_f32_e32 v178, v212, v212
	v_cvt_pk_bf16_f32 v182, v210, v211
	v_cvt_pk_bf16_f32 v183, v212, v213
	v_add_f32_e32 v177, v177, v178
	v_add_f32_e32 v179, v179, v177
	global_store_dwordx2 v175, v[182:183], s[18:19] offset:288
	ds_bpermute_b32 v177, v141, v179
	s_waitcnt lgkmcnt(0)
	v_add_f32_e32 v179, v179, v177
	ds_bpermute_b32 v178, v172, v179
	s_waitcnt lgkmcnt(0)
	v_add_f32_e32 v179, v179, v178
	s_and_saveexec_b64 s[52:53], s[4:5]
	global_store_dword v176, v179, s[14:15]
	s_mov_b64 exec, s[52:53]
	v_add_u32_e32 v174, 0xb0000, v138
	v_add_u32_e32 v175, 0x58000, v139
	v_add_u32_e32 v176, 0x2c00, v140
	s_waitcnt vmcnt(21)
	v_pk_add_f32 v[216:217], v[16:17], v[216:217]
	v_pk_add_f32 v[214:215], v[14:15], v[214:215]
	global_store_dwordx4 v174, v[214:217], s[84:85]
	v_mul_f32_e32 v178, v217, v217
	v_mul_f32_e32 v177, v215, v215
	v_fmac_f32_e32 v177, v214, v214
	v_fmac_f32_e32 v178, v216, v216
	v_cvt_pk_bf16_f32 v180, v214, v215
	v_cvt_pk_bf16_f32 v181, v216, v217
	v_add_f32_e32 v179, v177, v178
	global_store_dwordx2 v175, v[180:181], s[18:19]
	s_waitcnt vmcnt(22)
	v_pk_add_f32 v[220:221], v[12:13], v[220:221]
	v_pk_add_f32 v[218:219], v[10:11], v[218:219]
	global_store_dwordx4 v174, v[218:221], s[84:85] offset:64
	v_mul_f32_e32 v178, v221, v221
	v_mul_f32_e32 v177, v219, v219
	v_fmac_f32_e32 v177, v218, v218
	v_fmac_f32_e32 v178, v220, v220
	v_cvt_pk_bf16_f32 v182, v218, v219
	v_cvt_pk_bf16_f32 v183, v220, v221
	v_add_f32_e32 v177, v177, v178
	v_add_f32_e32 v179, v179, v177
	global_store_dwordx2 v175, v[182:183], s[18:19] offset:32
	s_waitcnt vmcnt(23)
	v_pk_add_f32 v[224:225], v[8:9], v[224:225]
	v_pk_add_f32 v[222:223], v[6:7], v[222:223]
	global_store_dwordx4 v174, v[222:225], s[84:85] offset:512
	v_mul_f32_e32 v178, v225, v225
	v_mul_f32_e32 v177, v223, v223
	v_fmac_f32_e32 v177, v222, v222
	v_fmac_f32_e32 v178, v224, v224
	v_cvt_pk_bf16_f32 v180, v222, v223
	v_cvt_pk_bf16_f32 v181, v224, v225
	v_add_f32_e32 v177, v177, v178
	v_add_f32_e32 v179, v179, v177
	global_store_dwordx2 v175, v[180:181], s[18:19] offset:256
	s_waitcnt vmcnt(24)
	v_pk_add_f32 v[228:229], v[4:5], v[228:229]
	v_pk_add_f32 v[226:227], v[2:3], v[226:227]
	global_store_dwordx4 v174, v[226:229], s[84:85] offset:576
	v_mul_f32_e32 v178, v229, v229
	v_mul_f32_e32 v177, v227, v227
	v_fmac_f32_e32 v177, v226, v226
	v_fmac_f32_e32 v178, v228, v228
	v_cvt_pk_bf16_f32 v182, v226, v227
	v_cvt_pk_bf16_f32 v183, v228, v229
	v_add_f32_e32 v177, v177, v178
	v_add_f32_e32 v179, v179, v177
	global_store_dwordx2 v175, v[182:183], s[18:19] offset:288
	ds_bpermute_b32 v177, v141, v179
	s_waitcnt lgkmcnt(0)
	v_add_f32_e32 v179, v179, v177
	ds_bpermute_b32 v178, v172, v179
	s_waitcnt lgkmcnt(0)
	v_add_f32_e32 v179, v179, v178
	s_and_saveexec_b64 s[52:53], s[4:5]
	global_store_dword v176, v179, s[14:15]
	s_mov_b64 exec, s[52:53]
	s_branch .Lepi8_end
;     __device__ __forceinline__ void operator()(const f32x4 (&acc)[2][2][4][2], const pg8::Unit& u, int wr, int wc, int fr, int fq, LAS unsigned char*) const {
;         const int row0 = u.pm * 256 + wr * 64 + fr, col0 = u.pn * 256 + wc * 32 + 4 * fq;
; #pragma unroll
;         for (int ai = 0; ai < 2; ++ai)
; #pragma unroll
;             for (int m = 0; m < 4; ++m) {
;                 const int row = row0 + ai * 128 + m * 16; const size_t off = (size_t)row * DM + col0; float q = 0.f;
; #pragma unroll
;                 for (int bj = 0; bj < 2; ++bj)
; #pragma unroll
;                     for (int n = 0; n < 2; ++n) { const size_t o = off + bj * 128 + n * 16; const f32x4 xv = *(const f32x4*)(xin + o) + acc[ai][bj][m][n]; *(f32x4*)(xout + o) = xv;
.Lepi8_lean:
	v_lshl_add_u32 v136, s68, 8, v142
	v_lshl_or_b32 v137, s28, 8, v144
	v_lshl_add_u32 v139, v136, 10, v137
	v_lshlrev_b32_e32 v138, 2, v139
	global_load_dwordx4 v[198:201], v138, s[12:13]
	global_load_dwordx4 v[202:205], v138, s[12:13] offset:64
	global_load_dwordx4 v[206:209], v138, s[12:13] offset:512
	global_load_dwordx4 v[210:213], v138, s[12:13] offset:576
	v_add_u32_e32 v173, 0x10000, v138
	global_load_dwordx4 v[214:217], v173, s[12:13]
	global_load_dwordx4 v[218:221], v173, s[12:13] offset:64
	global_load_dwordx4 v[222:225], v173, s[12:13] offset:512
	global_load_dwordx4 v[226:229], v173, s[12:13] offset:576
	v_add_u32_e32 v173, 0x20000, v138
	global_load_dwordx4 v[156:159], v173, s[12:13]
	global_load_dwordx4 v[160:163], v173, s[12:13] offset:64
	global_load_dwordx4 v[164:167], v173, s[12:13] offset:512
	global_load_dwordx4 v[168:171], v173, s[12:13] offset:576
	v_mov_b32_e32 v174, v138
	s_waitcnt vmcnt(11)
	v_pk_add_f32 v[200:201], v[128:129], v[200:201]
	v_pk_add_f32 v[198:199], v[126:127], v[198:199]
	global_store_dwordx4 v174, v[198:201], s[84:85]
	s_waitcnt vmcnt(11)
	v_pk_add_f32 v[204:205], v[124:125], v[204:205]
	v_pk_add_f32 v[202:203], v[122:123], v[202:203]
	global_store_dwordx4 v174, v[202:205], s[84:85] offset:64
	s_waitcnt vmcnt(11)
	v_pk_add_f32 v[208:209], v[120:121], v[208:209]
	v_pk_add_f32 v[206:207], v[118:119], v[206:207]
	global_store_dwordx4 v174, v[206:209], s[84:85] offset:512
	s_waitcnt vmcnt(11)
	v_pk_add_f32 v[212:213], v[116:117], v[212:213]
	v_pk_add_f32 v[210:211], v[114:115], v[210:211]
	global_store_dwordx4 v174, v[210:213], s[84:85] offset:576
	v_add_u32_e32 v173, 0x30000, v138
	global_load_dwordx4 v[198:201], v173, s[12:13]
	global_load_dwordx4 v[202:205], v173, s[12:13] offset:64
	global_load_dwordx4 v[206:209], v173, s[12:13] offset:512
	global_load_dwordx4 v[210:213], v173, s[12:13] offset:576
	v_add_u32_e32 v174, 0x10000, v138
	s_waitcnt vmcnt(15)
	v_pk_add_f32 v[216:217], v[112:113], v[216:217]
	v_pk_add_f32 v[214:215], v[110:111], v[214:215]
	global_store_dwordx4 v174, v[214:217], s[84:85]
	s_waitcnt vmcnt(15)
	v_pk_add_f32 v[220:221], v[108:109], v[220:221]
	v_pk_add_f32 v[218:219], v[106:107], v[218:219]
	global_store_dwordx4 v174, v[218:221], s[84:85] offset:64
	s_waitcnt vmcnt(15)
	v_pk_add_f32 v[224:225], v[104:105], v[224:225]
	v_pk_add_f32 v[222:223], v[102:103], v[222:223]
	global_store_dwordx4 v174, v[222:225], s[84:85] offset:512
	s_waitcnt vmcnt(15)
	v_pk_add_f32 v[228:229], v[100:101], v[228:229]
	v_pk_add_f32 v[226:227], v[98:99], v[226:227]
	global_store_dwordx4 v174, v[226:229], s[84:85] offset:576
	v_add_u32_e32 v173, 0x80000, v138
	global_load_dwordx4 v[214:217], v173, s[12:13]
	global_load_dwordx4 v[218:221], v173, s[12:13] offset:64
	global_load_dwordx4 v[222:225], v173, s[12:13] offset:512
	global_load_dwordx4 v[226:229], v173, s[12:13] offset:576
	v_add_u32_e32 v174, 0x20000, v138
	s_waitcnt vmcnt(19)
	v_pk_add_f32 v[158:159], v[96:97], v[158:159]
	v_pk_add_f32 v[156:157], v[94:95], v[156:157]
	global_store_dwordx4 v174, v[156:159], s[84:85]
	s_waitcnt vmcnt(19)
	v_pk_add_f32 v[162:163], v[92:93], v[162:163]
	v_pk_add_f32 v[160:161], v[90:91], v[160:161]
	global_store_dwordx4 v174, v[160:163], s[84:85] offset:64
	s_waitcnt vmcnt(19)
	v_pk_add_f32 v[166:167], v[88:89], v[166:167]
	v_pk_add_f32 v[164:165], v[86:87], v[164:165]
	global_store_dwordx4 v174, v[164:167], s[84:85] offset:512
	s_waitcnt vmcnt(19)
	v_pk_add_f32 v[170:171], v[84:85], v[170:171]
	v_pk_add_f32 v[168:169], v[82:83], v[168:169]
	global_store_dwordx4 v174, v[168:171], s[84:85] offset:576
	v_add_u32_e32 v173, 0x90000, v138
	global_load_dwordx4 v[156:159], v173, s[12:13]
	global_load_dwordx4 v[160:163], v173, s[12:13] offset:64
	global_load_dwordx4 v[164:167], v173, s[12:13] offset:512
	global_load_dwordx4 v[168:171], v173, s[12:13] offset:576
	v_add_u32_e32 v174, 0x30000, v138
	s_waitcnt vmcnt(19)
	v_pk_add_f32 v[200:201], v[80:81], v[200:201]
	v_pk_add_f32 v[198:199], v[78:79], v[198:199]
	global_store_dwordx4 v174, v[198:201], s[84:85]
	s_waitcnt vmcnt(19)
; #define PG8_BAR __builtin_amdgcn_s_barrier()
; template <class Epi, class Sched>
; __device__ __forceinline__ void gemm_phase(LAS unsigned char* lds, const Gemm g, const Sched& S, const Epi& E, const int tid) {
;     ...
;         if (!has_next) break;
;         if (!(Epi::CHAIN && nxt.seg != 0))
; #pragma unroll
;         for (int a = 0; a < 2; ++a)
; #pragma unroll
;             for (int b = 0; b < 2; ++b)
; #pragma unroll
;                 for (int m = 0; m < 4; ++m)
; #pragma unroll
;                     for (int n = 0; n < 2; ++n) acc[a][b][m][n] = (f32x4){0.f, 0.f, 0.f, 0.f};
;         cur = nxt; cA = nA; cB = nB; ++ui;
;         E.prep(cur, lds + STAGE_BYTES + (ui & 1) * 2048, tid);
;         if (wr == 1) PG8_BAR;
;     }
;     __device__ __forceinline__ void operator()(const f32x4 (&acc)[2][2][4][2], const pg8::Unit& u, int wr, int wc, int fr, int fq, LAS unsigned char*) const {
;         const int row0 = u.pm * 256 + wr * 64 + fr, col0 = u.pn * 256 + wc * 32 + 4 * fq;
; #pragma unroll
;         for (int ai = 0; ai < 2; ++ai)
; #pragma unroll
;             for (int m = 0; m < 4; ++m) {
;                 const int row = row0 + ai * 128 + m * 16; const size_t off = (size_t)row * DM + col0; float q = 0.f;
; #pragma unroll
;                 for (int bj = 0; bj < 2; ++bj)
; #pragma unroll
;                     for (int n = 0; n < 2; ++n) { const size_t o = off + bj * 128 + n * 16; const f32x4 xv = *(const f32x4*)(xin + o) + acc[ai][bj][m][n]; *(f32x4*)(xout + o) = xv;
	v_pk_add_f32 v[204:205], v[76:77], v[204:205]
	v_pk_add_f32 v[202:203], v[74:75], v[202:203]
	global_store_dwordx4 v174, v[202:205], s[84:85] offset:64
	s_waitcnt vmcnt(19)
	v_pk_add_f32 v[208:209], v[72:73], v[208:209]
	v_pk_add_f32 v[206:207], v[70:71], v[206:207]
	global_store_dwordx4 v174, v[206:209], s[84:85] offset:512
	s_waitcnt vmcnt(19)
	v_pk_add_f32 v[212:213], v[68:69], v[212:213]
	v_pk_add_f32 v[210:211], v[66:67], v[210:211]
	global_store_dwordx4 v174, v[210:213], s[84:85] offset:576
	v_add_u32_e32 v173, 0xa0000, v138
	global_load_dwordx4 v[198:201], v173, s[12:13]
	global_load_dwordx4 v[202:205], v173, s[12:13] offset:64
	global_load_dwordx4 v[206:209], v173, s[12:13] offset:512
	global_load_dwordx4 v[210:213], v173, s[12:13] offset:576
	v_add_u32_e32 v174, 0x80000, v138
	s_waitcnt vmcnt(19)
	v_pk_add_f32 v[216:217], v[64:65], v[216:217]
	v_pk_add_f32 v[214:215], v[62:63], v[214:215]
	global_store_dwordx4 v174, v[214:217], s[84:85]
	s_waitcnt vmcnt(19)
	v_pk_add_f32 v[220:221], v[60:61], v[220:221]
	v_pk_add_f32 v[218:219], v[58:59], v[218:219]
	global_store_dwordx4 v174, v[218:221], s[84:85] offset:64
	s_waitcnt vmcnt(19)
	v_pk_add_f32 v[224:225], v[56:57], v[224:225]
	v_pk_add_f32 v[222:223], v[54:55], v[222:223]
	global_store_dwordx4 v174, v[222:225], s[84:85] offset:512
	s_waitcnt vmcnt(19)
	v_pk_add_f32 v[228:229], v[52:53], v[228:229]
	v_pk_add_f32 v[226:227], v[50:51], v[226:227]
	global_store_dwordx4 v174, v[226:229], s[84:85] offset:576
	v_add_u32_e32 v173, 0xb0000, v138
	global_load_dwordx4 v[214:217], v173, s[12:13]
	global_load_dwordx4 v[218:221], v173, s[12:13] offset:64
	global_load_dwordx4 v[222:225], v173, s[12:13] offset:512
	global_load_dwordx4 v[226:229], v173, s[12:13] offset:576
	v_add_u32_e32 v174, 0x90000, v138
	s_waitcnt vmcnt(19)
	v_pk_add_f32 v[158:159], v[48:49], v[158:159]
	v_pk_add_f32 v[156:157], v[46:47], v[156:157]
	global_store_dwordx4 v174, v[156:159], s[84:85]
	s_waitcnt vmcnt(19)
	v_pk_add_f32 v[162:163], v[44:45], v[162:163]
	v_pk_add_f32 v[160:161], v[42:43], v[160:161]
	global_store_dwordx4 v174, v[160:163], s[84:85] offset:64
	s_waitcnt vmcnt(19)
	v_pk_add_f32 v[166:167], v[40:41], v[166:167]
	v_pk_add_f32 v[164:165], v[38:39], v[164:165]
	global_store_dwordx4 v174, v[164:167], s[84:85] offset:512
	s_waitcnt vmcnt(19)
	v_pk_add_f32 v[170:171], v[36:37], v[170:171]
	v_pk_add_f32 v[168:169], v[34:35], v[168:169]
	global_store_dwordx4 v174, v[168:171], s[84:85] offset:576
	v_add_u32_e32 v174, 0xa0000, v138
	s_waitcnt vmcnt(15)
	v_pk_add_f32 v[200:201], v[32:33], v[200:201]
	v_pk_add_f32 v[198:199], v[30:31], v[198:199]
	global_store_dwordx4 v174, v[198:201], s[84:85]
	s_waitcnt vmcnt(15)
	v_pk_add_f32 v[204:205], v[28:29], v[204:205]
	v_pk_add_f32 v[202:203], v[26:27], v[202:203]
	global_store_dwordx4 v174, v[202:205], s[84:85] offset:64
	s_waitcnt vmcnt(15)
	v_pk_add_f32 v[208:209], v[24:25], v[208:209]
	v_pk_add_f32 v[206:207], v[22:23], v[206:207]
	global_store_dwordx4 v174, v[206:209], s[84:85] offset:512
	s_waitcnt vmcnt(15)
	v_pk_add_f32 v[212:213], v[20:21], v[212:213]
	v_pk_add_f32 v[210:211], v[18:19], v[210:211]
	global_store_dwordx4 v174, v[210:213], s[84:85] offset:576
	v_add_u32_e32 v174, 0xb0000, v138
	s_waitcnt vmcnt(11)
	v_pk_add_f32 v[216:217], v[16:17], v[216:217]
	v_pk_add_f32 v[214:215], v[14:15], v[214:215]
	global_store_dwordx4 v174, v[214:217], s[84:85]
	s_waitcnt vmcnt(11)
	v_pk_add_f32 v[220:221], v[12:13], v[220:221]
	v_pk_add_f32 v[218:219], v[10:11], v[218:219]
	global_store_dwordx4 v174, v[218:221], s[84:85] offset:64
	s_waitcnt vmcnt(11)
	v_pk_add_f32 v[224:225], v[8:9], v[224:225]
	v_pk_add_f32 v[222:223], v[6:7], v[222:223]
	global_store_dwordx4 v174, v[222:225], s[84:85] offset:512
	s_waitcnt vmcnt(11)
	v_pk_add_f32 v[228:229], v[4:5], v[228:229]
	v_pk_add_f32 v[226:227], v[2:3], v[226:227]
	global_store_dwordx4 v174, v[226:229], s[84:85] offset:576
.Lepi8_end:
	s_and_b64 vcc, exec, s[6:7]
	s_mov_b64 s[6:7], -1
	s_cbranch_vccnz .LBB0_406
	s_andn2_b64 vcc, exec, s[16:17]
	s_cbranch_vccnz .LBB0_405
	s_barrier
	s_branch .LBB0_405
